# v44 plus MLA attention epilogue store widening: 64 two-byte global stores per lane replaced by per-wave LDS transpose and 8 global_store_dwordx4
# baseline (speedup 1.0000x reference)
; #define GAS __attribute__((address_space(1)))
; __device__ __forceinline__ unsigned f2bf(float f) { unsigned u = __builtin_bit_cast(unsigned, f); return (u + 0x7fffu + ((u >> 16) & 1u)) >> 16; }
; __device__ __forceinline__ int crow(int r, int hi) { return (r & 3) + 8 * (r >> 2) + 4 * hi; }
; __device__ __forceinline__ void attn_body(const GAS bf16* __restrict__ Qb, const int ldq, const GAS bf16* __restrict__ Kn, const GAS bf16* __restrict__ Vh, const int ldkv, const GAS bf16* __restrict__ Kr, ...
;     ...
;   if (hi == 0) li_l[r32] = l_reg; asm volatile("s_waitcnt lgkmcnt(0)" ::: "memory");
;   float rli[16];
; #pragma unroll
;   for (int r = 0; r < 16; ++r) rli[r] = __builtin_amdgcn_rcpf(li_l[crow(r, hi)]);
;   GAS bf16* Ow = Ob + (size_t)(wid * QBLK) * ldo;
; #pragma unroll
;   for (int r = 0; r < 16; ++r) { const int orow = crow(r, hi);
; #pragma unroll
;     for (int d0 = 0; d0 < 4; ++d0) Ow[(size_t)orow * ldo + d0 * 32 + r32] = (bf16)f2bf(o[d0][r] * rli[r]); }
.LBB0_2630:
	s_or_b64 exec, exec, s[4:5]
	s_waitcnt lgkmcnt(0)
	v_add_u32_e32 v72, v167, v164
	ds_read_b128 v[64:67], v72
	ds_read2_b32 v[68:69], v72 offset0:8 offset1:9
	s_lshl_b64 s[0:1], s[46:47], 12
	s_add_u32 s0, s70, s0
	s_addc_u32 s1, s71, s1
	s_waitcnt lgkmcnt(1)
	v_rcp_f32_e32 v73, v64
	v_rcp_f32_e32 v74, v65
	ds_read2_b32 v[64:65], v72 offset0:10 offset1:11
	v_rcp_f32_e32 v75, v66
	v_rcp_f32_e32 v76, v67
	s_waitcnt lgkmcnt(1)
	v_rcp_f32_e32 v77, v68
	v_rcp_f32_e32 v78, v69
	ds_read2_b32 v[66:67], v72 offset0:16 offset1:17
	ds_read2_b32 v[68:69], v72 offset0:18 offset1:19
	ds_read2_b32 v[70:71], v72 offset0:24 offset1:25
	s_waitcnt lgkmcnt(3)
	v_rcp_f32_e32 v79, v64
	v_rcp_f32_e32 v80, v65
	ds_read2_b32 v[64:65], v72 offset0:26 offset1:27
	s_lshl_b32 s2, s53, 8
	s_add_u32 s2, s0, s2
	v_ashrrev_i32_e32 v167, 31, v166
	s_addc_u32 s3, s1, 0
	s_waitcnt lgkmcnt(0)
	v_rcp_f32_e32 v72, v64
	v_rcp_f32_e32 v83, v65
	v_lshlrev_b64 v[64:65], 12, v[166:167]
	v_lshl_add_u64 v[64:65], s[2:3], 0, v[64:65]
	v_lshlrev_b32_e32 v164, 1, v190
	v_rcp_f32_e32 v81, v66
	v_rcp_f32_e32 v82, v67
	v_lshlrev_b32_e32 v66, 14, v191
	v_lshl_add_u64 v[64:65], v[64:65], 0, v[164:165]
	v_mov_b32_e32 v67, v165
	v_mul_f32_e32 v0, v0, v73
	v_lshl_add_u64 v[64:65], v[64:65], 0, v[66:67]
	s_lshr_b32 s100, s33, 6
	s_mul_i32 s100, s100, 0x1200
	s_add_i32 s100, s100, 0x15000
	s_movk_i32 s101, 0x110
	v_mul_u32_u24_e32 v128, 0x440, v191
	v_lshl_add_u32 v128, v190, 1, v128
	v_add_u32_e32 v128, s100, v128
	v_and_b32_e32 v131, 63, v188
	v_lshrrev_b32_e32 v132, 4, v131
	v_and_b32_e32 v131, 15, v131
	v_lshlrev_b32_e32 v131, 4, v131
	v_mad_u32_u24 v129, v132, s101, v131
	v_add_u32_e32 v129, s100, v129
	v_lshl_add_u32 v130, v132, 12, v131
	s_lshl_b32 s100, s33, 11
	s_add_u32 s98, s2, s100
	s_addc_u32 s99, s3, 0
	v_bfe_u32 v66, v0, 16, 1
	v_add3_u32 v0, v0, v66, s81
	ds_write_b16_d16_hi v128, v0 offset:0
	v_mul_f32_e32 v0, v48, v73
	v_bfe_u32 v48, v0, 16, 1
	v_add3_u32 v0, v0, v48, s81
	ds_write_b16_d16_hi v128, v0 offset:64
	v_mul_f32_e32 v0, v32, v73
	v_bfe_u32 v32, v0, 16, 1
	v_add3_u32 v0, v0, v32, s81
	ds_write_b16_d16_hi v128, v0 offset:128
	v_mul_f32_e32 v0, v16, v73
	v_bfe_u32 v16, v0, 16, 1
	v_add3_u32 v0, v0, v16, s81
	ds_write_b16_d16_hi v128, v0 offset:192
	v_mul_f32_e32 v0, v1, v74
	v_bfe_u32 v1, v0, 16, 1
	s_movk_i32 s0, 0x1000
	v_add3_u32 v16, v0, v1, s81
	v_add_co_u32_e32 v0, vcc, s0, v64
	s_movk_i32 s0, 0x3000
	s_nop 0
	v_addc_co_u32_e32 v1, vcc, 0, v65, vcc
	v_add_co_u32_e32 v66, vcc, s76, v64
	v_rcp_f32_e32 v68, v68
	s_nop 0
	v_addc_co_u32_e32 v67, vcc, 0, v65, vcc
	ds_write_b16_d16_hi v128, v16 offset:272
	v_mul_f32_e32 v16, v49, v74
	v_bfe_u32 v32, v16, 16, 1
	v_add3_u32 v16, v16, v32, s81
	ds_write_b16_d16_hi v128, v16 offset:336
	v_mul_f32_e32 v16, v33, v74
	v_bfe_u32 v32, v16, 16, 1
	v_add3_u32 v16, v16, v32, s81
	ds_write_b16_d16_hi v128, v16 offset:400
	v_mul_f32_e32 v16, v17, v74
	v_bfe_u32 v17, v16, 16, 1
	v_add3_u32 v16, v16, v17, s81
	ds_write_b16_d16_hi v128, v16 offset:464
	v_mul_f32_e32 v0, v2, v75
	v_bfe_u32 v1, v0, 16, 1
	v_add3_u32 v0, v0, v1, s81
	ds_write_b16_d16_hi v128, v0 offset:544
	v_mul_f32_e32 v0, v50, v75
	v_bfe_u32 v1, v0, 16, 1
	v_add3_u32 v0, v0, v1, s81
	ds_write_b16_d16_hi v128, v0 offset:608
	v_mul_f32_e32 v0, v34, v75
	v_bfe_u32 v1, v0, 16, 1
	v_add3_u32 v0, v0, v1, s81
	ds_write_b16_d16_hi v128, v0 offset:672
	v_mul_f32_e32 v0, v18, v75
	v_bfe_u32 v1, v0, 16, 1
	v_add3_u32 v0, v0, v1, s81
	ds_write_b16_d16_hi v128, v0 offset:736
	v_mul_f32_e32 v0, v3, v76
	v_bfe_u32 v1, v0, 16, 1
	v_add3_u32 v2, v0, v1, s81
	v_add_co_u32_e32 v0, vcc, s0, v64
	s_mov_b32 s0, 0x8000
	s_nop 0
	v_addc_co_u32_e32 v1, vcc, 0, v65, vcc
	ds_write_b16_d16_hi v128, v2 offset:816
	v_mul_f32_e32 v2, v51, v76
	v_bfe_u32 v3, v2, 16, 1
	v_add3_u32 v2, v2, v3, s81
	ds_write_b16_d16_hi v128, v2 offset:880
	v_mul_f32_e32 v2, v35, v76
	v_bfe_u32 v3, v2, 16, 1
	v_add3_u32 v2, v2, v3, s81
	ds_write_b16_d16_hi v128, v2 offset:944
	v_mul_f32_e32 v2, v19, v76
	v_bfe_u32 v3, v2, 16, 1
	v_add3_u32 v2, v2, v3, s81
	ds_write_b16_d16_hi v128, v2 offset:1008
	v_mul_f32_e32 v0, v4, v77
	v_bfe_u32 v1, v0, 16, 1
	v_add3_u32 v4, v0, v1, s81
	v_add_co_u32_e32 v0, vcc, s0, v64
	s_mov_b32 s0, 0x9000
	s_nop 0
	v_addc_co_u32_e32 v1, vcc, 0, v65, vcc
	v_add_co_u32_e32 v2, vcc, s0, v64
	s_mov_b32 s0, 0xa000
	s_nop 0
	v_addc_co_u32_e32 v3, vcc, 0, v65, vcc
	ds_write_b16_d16_hi v128, v4 offset:2176
	v_mul_f32_e32 v4, v52, v77
	v_bfe_u32 v16, v4, 16, 1
	v_add3_u32 v4, v4, v16, s81
	ds_write_b16_d16_hi v128, v4 offset:2240
	v_mul_f32_e32 v4, v36, v77
	v_bfe_u32 v16, v4, 16, 1
	v_add3_u32 v4, v4, v16, s81
	ds_write_b16_d16_hi v128, v4 offset:2304
	v_mul_f32_e32 v4, v20, v77
	v_bfe_u32 v16, v4, 16, 1
	v_add3_u32 v4, v4, v16, s81
	ds_write_b16_d16_hi v128, v4 offset:2368
	v_mul_f32_e32 v0, v5, v78
	v_bfe_u32 v1, v0, 16, 1
	v_add3_u32 v0, v0, v1, s81
	ds_write_b16_d16_hi v128, v0 offset:2448
	v_mul_f32_e32 v0, v53, v78
	v_bfe_u32 v1, v0, 16, 1
	v_add3_u32 v0, v0, v1, s81
	ds_write_b16_d16_hi v128, v0 offset:2512
	v_mul_f32_e32 v0, v37, v78
	v_bfe_u32 v1, v0, 16, 1
	v_add3_u32 v0, v0, v1, s81
	ds_write_b16_d16_hi v128, v0 offset:2576
	v_mul_f32_e32 v0, v21, v78
	v_bfe_u32 v1, v0, 16, 1
	v_add3_u32 v0, v0, v1, s81
	ds_write_b16_d16_hi v128, v0 offset:2640
	v_mul_f32_e32 v0, v6, v79
	v_bfe_u32 v1, v0, 16, 1
	v_add3_u32 v4, v0, v1, s81
	v_add_co_u32_e32 v0, vcc, s0, v64
	s_mov_b32 s0, 0xb000
	s_nop 0
	v_addc_co_u32_e32 v1, vcc, 0, v65, vcc
	v_add_co_u32_e32 v2, vcc, s0, v64
	s_mov_b32 s0, 0x10000
	s_nop 0
	v_addc_co_u32_e32 v3, vcc, 0, v65, vcc
	ds_write_b16_d16_hi v128, v4 offset:2720
	v_mul_f32_e32 v4, v54, v79
	v_bfe_u32 v5, v4, 16, 1
	v_add3_u32 v4, v4, v5, s81
	ds_write_b16_d16_hi v128, v4 offset:2784
	v_mul_f32_e32 v4, v38, v79
	v_bfe_u32 v5, v4, 16, 1
	v_add3_u32 v4, v4, v5, s81
	ds_write_b16_d16_hi v128, v4 offset:2848
	v_mul_f32_e32 v4, v22, v79
	v_bfe_u32 v5, v4, 16, 1
	v_add3_u32 v4, v4, v5, s81
	ds_write_b16_d16_hi v128, v4 offset:2912
	v_mul_f32_e32 v0, v7, v80
	v_bfe_u32 v1, v0, 16, 1
	v_add3_u32 v0, v0, v1, s81
	ds_write_b16_d16_hi v128, v0 offset:2992
	v_mul_f32_e32 v0, v55, v80
	v_bfe_u32 v1, v0, 16, 1
	v_add3_u32 v0, v0, v1, s81
	ds_write_b16_d16_hi v128, v0 offset:3056
	v_mul_f32_e32 v0, v39, v80
	v_bfe_u32 v1, v0, 16, 1
	v_add3_u32 v0, v0, v1, s81
	ds_write_b16_d16_hi v128, v0 offset:3120
	v_mul_f32_e32 v0, v23, v80
	v_bfe_u32 v1, v0, 16, 1
	v_add3_u32 v0, v0, v1, s81
	ds_write_b16_d16_hi v128, v0 offset:3184
	s_waitcnt lgkmcnt(0)
; #define GAS __attribute__((address_space(1)))
; __device__ __forceinline__ unsigned f2bf(float f) { unsigned u = __builtin_bit_cast(unsigned, f); return (u + 0x7fffu + ((u >> 16) & 1u)) >> 16; }
; __device__ __forceinline__ int crow(int r, int hi) { return (r & 3) + 8 * (r >> 2) + 4 * hi; }
; __device__ __forceinline__ void attn_body(const GAS bf16* __restrict__ Qb, const int ldq, const GAS bf16* __restrict__ Kn, const GAS bf16* __restrict__ Vh, const int ldkv, const GAS bf16* __restrict__ Kr, ...
;     ...
;   for (int r = 0; r < 16; ++r) rli[r] = __builtin_amdgcn_rcpf(li_l[crow(r, hi)]);
;   GAS bf16* Ow = Ob + (size_t)(wid * QBLK) * ldo;
; #pragma unroll
;   for (int r = 0; r < 16; ++r) { const int orow = crow(r, hi);
; #pragma unroll
;     for (int d0 = 0; d0 < 4; ++d0) Ow[(size_t)orow * ldo + d0 * 32 + r32] = (bf16)f2bf(o[d0][r] * rli[r]); }
;   __syncthreads();
	ds_read_b128 v[112:115], v129
	ds_read_b128 v[116:119], v129 offset:1088
	ds_read_b128 v[120:123], v129 offset:2176
	ds_read_b128 v[124:127], v129 offset:3264
	s_waitcnt lgkmcnt(3)
	global_store_dwordx4 v130, v[112:115], s[98:99]
	s_add_u32 s98, s98, 0x4000
	s_addc_u32 s99, s99, 0
	s_waitcnt lgkmcnt(2)
	global_store_dwordx4 v130, v[116:119], s[98:99]
	s_add_u32 s98, s98, 0x4000
	s_addc_u32 s99, s99, 0
	s_waitcnt lgkmcnt(1)
	global_store_dwordx4 v130, v[120:123], s[98:99]
	s_add_u32 s98, s98, 0x4000
	s_addc_u32 s99, s99, 0
	s_waitcnt lgkmcnt(0)
	global_store_dwordx4 v130, v[124:127], s[98:99]
	s_add_u32 s98, s98, 0x4000
	s_addc_u32 s99, s99, 0
	v_mul_f32_e32 v0, v8, v81
	v_bfe_u32 v1, v0, 16, 1
	v_add3_u32 v4, v0, v1, s81
	v_add_co_u32_e32 v0, vcc, s0, v64
	s_mov_b32 s0, 0x11000
	s_nop 0
	v_addc_co_u32_e32 v1, vcc, 0, v65, vcc
	v_add_co_u32_e32 v2, vcc, s0, v64
	s_mov_b32 s0, 0x12000
	s_nop 0
	v_addc_co_u32_e32 v3, vcc, 0, v65, vcc
	ds_write_b16_d16_hi v128, v4 offset:0
	v_mul_f32_e32 v4, v56, v81
	v_bfe_u32 v5, v4, 16, 1
	v_add3_u32 v4, v4, v5, s81
	ds_write_b16_d16_hi v128, v4 offset:64
	v_mul_f32_e32 v4, v40, v81
	v_bfe_u32 v5, v4, 16, 1
	v_add3_u32 v4, v4, v5, s81
	ds_write_b16_d16_hi v128, v4 offset:128
	v_mul_f32_e32 v4, v24, v81
	v_bfe_u32 v5, v4, 16, 1
	v_add3_u32 v4, v4, v5, s81
	ds_write_b16_d16_hi v128, v4 offset:192
	v_mul_f32_e32 v0, v9, v82
	v_bfe_u32 v1, v0, 16, 1
	v_add3_u32 v0, v0, v1, s81
	ds_write_b16_d16_hi v128, v0 offset:272
	v_mul_f32_e32 v0, v57, v82
	v_bfe_u32 v1, v0, 16, 1
	v_add3_u32 v0, v0, v1, s81
	ds_write_b16_d16_hi v128, v0 offset:336
	v_mul_f32_e32 v0, v41, v82
	v_bfe_u32 v1, v0, 16, 1
	v_add3_u32 v0, v0, v1, s81
	ds_write_b16_d16_hi v128, v0 offset:400
	v_mul_f32_e32 v0, v25, v82
	v_bfe_u32 v1, v0, 16, 1
	v_add3_u32 v0, v0, v1, s81
	ds_write_b16_d16_hi v128, v0 offset:464
	v_mul_f32_e32 v0, v10, v68
	v_bfe_u32 v1, v0, 16, 1
	v_add3_u32 v4, v0, v1, s81
	v_add_co_u32_e32 v0, vcc, s0, v64
	s_mov_b32 s0, 0x13000
	s_nop 0
	v_addc_co_u32_e32 v1, vcc, 0, v65, vcc
	v_add_co_u32_e32 v2, vcc, s0, v64
	v_rcp_f32_e32 v69, v69
	s_nop 0
	v_addc_co_u32_e32 v3, vcc, 0, v65, vcc
	ds_write_b16_d16_hi v128, v4 offset:544
	v_mul_f32_e32 v4, v58, v68
	v_bfe_u32 v5, v4, 16, 1
	v_add3_u32 v4, v4, v5, s81
	ds_write_b16_d16_hi v128, v4 offset:608
	v_mul_f32_e32 v4, v42, v68
	v_bfe_u32 v5, v4, 16, 1
	v_add3_u32 v4, v4, v5, s81
	ds_write_b16_d16_hi v128, v4 offset:672
	v_mul_f32_e32 v4, v26, v68
	v_bfe_u32 v5, v4, 16, 1
	v_add3_u32 v4, v4, v5, s81
	ds_write_b16_d16_hi v128, v4 offset:736
	v_mul_f32_e32 v0, v11, v69
	v_bfe_u32 v1, v0, 16, 1
	v_add3_u32 v0, v0, v1, s81
	ds_write_b16_d16_hi v128, v0 offset:816
	v_mul_f32_e32 v0, v59, v69
	v_bfe_u32 v1, v0, 16, 1
	v_add3_u32 v0, v0, v1, s81
	ds_write_b16_d16_hi v128, v0 offset:880
	v_mul_f32_e32 v0, v43, v69
	v_bfe_u32 v1, v0, 16, 1
	v_rcp_f32_e32 v70, v70
	v_add3_u32 v0, v0, v1, s81
	ds_write_b16_d16_hi v128, v0 offset:944
	v_mul_f32_e32 v0, v27, v69
	v_bfe_u32 v1, v0, 16, 1
	v_add3_u32 v0, v0, v1, s81
	ds_write_b16_d16_hi v128, v0 offset:1008
	v_mul_f32_e32 v0, v12, v70
	v_bfe_u32 v1, v0, 16, 1
	v_add3_u32 v4, v0, v1, s81
	v_add_co_u32_e32 v0, vcc, s82, v64
	v_rcp_f32_e32 v71, v71
	s_nop 0
	v_addc_co_u32_e32 v1, vcc, 0, v65, vcc
	v_add_co_u32_e32 v2, vcc, s83, v64
	s_add_i32 s13, s13, s86
	s_nop 0
	v_addc_co_u32_e32 v3, vcc, 0, v65, vcc
	ds_write_b16_d16_hi v128, v4 offset:2176
	v_mul_f32_e32 v4, v60, v70
	v_bfe_u32 v5, v4, 16, 1
	v_add3_u32 v4, v4, v5, s81
	ds_write_b16_d16_hi v128, v4 offset:2240
	v_mul_f32_e32 v4, v44, v70
	v_bfe_u32 v5, v4, 16, 1
	v_add3_u32 v4, v4, v5, s81
	ds_write_b16_d16_hi v128, v4 offset:2304
	v_mul_f32_e32 v4, v28, v70
	v_bfe_u32 v5, v4, 16, 1
	v_add3_u32 v4, v4, v5, s81
	ds_write_b16_d16_hi v128, v4 offset:2368
	v_mul_f32_e32 v0, v13, v71
	v_bfe_u32 v1, v0, 16, 1
	v_add3_u32 v0, v0, v1, s81
	ds_write_b16_d16_hi v128, v0 offset:2448
	v_mul_f32_e32 v0, v61, v71
	v_bfe_u32 v1, v0, 16, 1
	v_add3_u32 v0, v0, v1, s81
	ds_write_b16_d16_hi v128, v0 offset:2512
	v_mul_f32_e32 v0, v45, v71
	v_bfe_u32 v1, v0, 16, 1
	v_add3_u32 v0, v0, v1, s81
	ds_write_b16_d16_hi v128, v0 offset:2576
	v_mul_f32_e32 v0, v29, v71
	v_bfe_u32 v1, v0, 16, 1
	v_add3_u32 v0, v0, v1, s81
	ds_write_b16_d16_hi v128, v0 offset:2640
	v_mul_f32_e32 v0, v14, v72
	v_bfe_u32 v1, v0, 16, 1
	v_add3_u32 v4, v0, v1, s81
	v_add_co_u32_e32 v0, vcc, s97, v64
	s_cmp_lt_i32 s13, s21
	s_nop 0
	v_addc_co_u32_e32 v1, vcc, 0, v65, vcc
	v_add_co_u32_e32 v2, vcc, s52, v64
	s_nop 1
	v_addc_co_u32_e32 v3, vcc, 0, v65, vcc
	ds_write_b16_d16_hi v128, v4 offset:2720
	v_mul_f32_e32 v4, v62, v72
	v_bfe_u32 v5, v4, 16, 1
	v_add3_u32 v4, v4, v5, s81
	ds_write_b16_d16_hi v128, v4 offset:2784
	v_mul_f32_e32 v4, v46, v72
	v_bfe_u32 v5, v4, 16, 1
	v_add3_u32 v4, v4, v5, s81
	ds_write_b16_d16_hi v128, v4 offset:2848
	v_mul_f32_e32 v4, v30, v72
	v_bfe_u32 v5, v4, 16, 1
	v_add3_u32 v4, v4, v5, s81
	ds_write_b16_d16_hi v128, v4 offset:2912
	v_mul_f32_e32 v0, v15, v83
	v_bfe_u32 v1, v0, 16, 1
	v_add3_u32 v0, v0, v1, s81
	ds_write_b16_d16_hi v128, v0 offset:2992
	v_mul_f32_e32 v0, v63, v83
	v_bfe_u32 v1, v0, 16, 1
	v_add3_u32 v0, v0, v1, s81
	ds_write_b16_d16_hi v128, v0 offset:3056
	v_mul_f32_e32 v0, v47, v83
	v_bfe_u32 v1, v0, 16, 1
	v_add3_u32 v0, v0, v1, s81
	ds_write_b16_d16_hi v128, v0 offset:3120
	v_mul_f32_e32 v0, v31, v83
	v_bfe_u32 v1, v0, 16, 1
	v_add3_u32 v0, v0, v1, s81
	ds_write_b16_d16_hi v128, v0 offset:3184
	s_waitcnt lgkmcnt(0)
	ds_read_b128 v[112:115], v129
	ds_read_b128 v[116:119], v129 offset:1088
	ds_read_b128 v[120:123], v129 offset:2176
	ds_read_b128 v[124:127], v129 offset:3264
	s_waitcnt lgkmcnt(3)
	global_store_dwordx4 v130, v[112:115], s[98:99]
	s_add_u32 s98, s98, 0x4000
	s_addc_u32 s99, s99, 0
	s_waitcnt lgkmcnt(2)
	global_store_dwordx4 v130, v[116:119], s[98:99]
	s_add_u32 s98, s98, 0x4000
	s_addc_u32 s99, s99, 0
	s_waitcnt lgkmcnt(1)
	global_store_dwordx4 v130, v[120:123], s[98:99]
	s_add_u32 s98, s98, 0x4000
	s_addc_u32 s99, s99, 0
	s_waitcnt lgkmcnt(0)
	global_store_dwordx4 v130, v[124:127], s[98:99]
	s_add_u32 s98, s98, 0x4000
	s_addc_u32 s99, s99, 0
	s_cmp_lt_i32 s13, s21
	s_waitcnt vmcnt(63) expcnt(7) lgkmcnt(15)
	s_barrier
	s_cbranch_scc0 .LBB0_2663
